# XCD-aware static attention item mapping + ret_scan 8-deep batched loads on top of diff-loop reschedule
# speedup vs baseline: 1.0079x; 1.0079x over previous
_Z14fwd_megakernel6Params:
	s_mov_b32 s101, s2
	s_load_dwordx16 s[8:23], s[0:1], 0xc0
	s_load_dword s86, s[0:1], 0x108
	s_load_dwordx2 s[92:93], s[0:1], 0x100
	s_add_u32 s90, s0, 0x100
	v_writelane_b32 v252, s2, 0
	v_and_b32_e32 v184, 0x3ff, v0
	s_addc_u32 s91, s1, 0
	v_writelane_b32 v252, s3, 1
	v_cmp_ne_u32_e64 s[88:89], 0, v184
	v_cmp_eq_u32_e64 s[4:5], 0, v184
	s_mov_b64 s[2:3], exec
	s_nop 0
	v_writelane_b32 v252, s4, 2
	s_nop 1
	v_writelane_b32 v252, s5, 3
	s_and_b64 s[4:5], s[2:3], s[4:5]
	s_mov_b64 exec, s[4:5]
	s_cbranch_execz .LBB0_2
	v_mov_b32_e32 v2, 0
	v_mov_b32_e32 v3, v2
	v_mov_b32_e32 v4, v2
	v_mov_b32_e32 v5, v2
	v_mov_b32_e32 v1, 0x12000
	ds_write_b128 v1, v[2:5]

.Lrsb_chk:
	v_cmp_gt_u32_e64 s[0:1], 9, v3
	s_cmp_lg_u64 s[0:1], 0
	s_cbranch_scc1 .LBB0_674
	s_mov_b32 s0, 0xffff0000
	s_mov_b32 s1, -1
	v_mov_b64_e32 v[16:17], v[6:7]
	global_load_dword v14, v[16:17], off
	v_lshl_add_u64 v[16:17], v[16:17], 0, s[0:1]
	global_load_dword v15, v[16:17], off
	v_lshl_add_u64 v[16:17], v[16:17], 0, s[0:1]
	global_load_dword v18, v[16:17], off
	v_lshl_add_u64 v[16:17], v[16:17], 0, s[0:1]
	global_load_dword v19, v[16:17], off
	v_lshl_add_u64 v[16:17], v[16:17], 0, s[0:1]
	global_load_dword v20, v[16:17], off
	v_lshl_add_u64 v[16:17], v[16:17], 0, s[0:1]
	global_load_dword v21, v[16:17], off
	v_lshl_add_u64 v[16:17], v[16:17], 0, s[0:1]
	global_load_dword v22, v[16:17], off
	v_lshl_add_u64 v[16:17], v[16:17], 0, s[0:1]
	global_load_dword v5, v[16:17], off
	s_waitcnt vmcnt(7)
	global_store_dword v[6:7], v13, off
	v_fma_f32 v13, v1, v13, v14
	v_lshl_add_u64 v[6:7], v[6:7], 0, s[0:1]
	s_waitcnt vmcnt(7)
	global_store_dword v[6:7], v13, off
	v_fma_f32 v13, v1, v13, v15
	v_lshl_add_u64 v[6:7], v[6:7], 0, s[0:1]
	s_waitcnt vmcnt(7)
	global_store_dword v[6:7], v13, off
	v_fma_f32 v13, v1, v13, v18
	v_lshl_add_u64 v[6:7], v[6:7], 0, s[0:1]
	s_waitcnt vmcnt(7)
	global_store_dword v[6:7], v13, off
	v_fma_f32 v13, v1, v13, v19
	v_lshl_add_u64 v[6:7], v[6:7], 0, s[0:1]
	s_waitcnt vmcnt(7)
	global_store_dword v[6:7], v13, off
	v_fma_f32 v13, v1, v13, v20
	v_lshl_add_u64 v[6:7], v[6:7], 0, s[0:1]
	s_waitcnt vmcnt(7)
	global_store_dword v[6:7], v13, off
	v_fma_f32 v13, v1, v13, v21
	v_lshl_add_u64 v[6:7], v[6:7], 0, s[0:1]
	s_waitcnt vmcnt(7)
	global_store_dword v[6:7], v13, off
	v_fma_f32 v13, v1, v13, v22
	v_lshl_add_u64 v[6:7], v[6:7], 0, s[0:1]
	s_waitcnt vmcnt(7)
	global_store_dword v[6:7], v13, off
	v_fma_f32 v13, v1, v13, v5
	v_lshl_add_u64 v[6:7], v[6:7], 0, s[0:1]
	v_add_u32_e32 v3, -8, v3
	v_cmp_ne_u32_e64 s[0:1], 1, v3
	s_cmp_lg_u64 s[0:1], 0
	s_cbranch_scc1 .Lrsb_chk
	s_branch .Lrsb_done

.Lrsb_done:
	s_or_b64 exec, exec, s[20:21]
	s_andn2_saveexec_b64 s[18:19], s[18:19]
	s_cbranch_execnz .LBB0_678

.Lrsf_chk:
	v_cmp_gt_u32_e64 s[0:1], 8, v11
	s_cmp_lg_u64 s[0:1], 0
	s_cbranch_scc1 .LBB0_679
	s_mov_b64 s[0:1], 0x10000
	v_mov_b64_e32 v[16:17], v[6:7]
	global_load_dword v14, v[16:17], off
	v_lshl_add_u64 v[16:17], v[16:17], 0, s[0:1]
	global_load_dword v15, v[16:17], off
	v_lshl_add_u64 v[16:17], v[16:17], 0, s[0:1]
	global_load_dword v18, v[16:17], off
	v_lshl_add_u64 v[16:17], v[16:17], 0, s[0:1]
	global_load_dword v19, v[16:17], off
	v_lshl_add_u64 v[16:17], v[16:17], 0, s[0:1]
	global_load_dword v20, v[16:17], off
	v_lshl_add_u64 v[16:17], v[16:17], 0, s[0:1]
	global_load_dword v21, v[16:17], off
	v_lshl_add_u64 v[16:17], v[16:17], 0, s[0:1]
	global_load_dword v22, v[16:17], off
	v_lshl_add_u64 v[16:17], v[16:17], 0, s[0:1]
	global_load_dword v5, v[16:17], off
	s_waitcnt vmcnt(7)
	global_store_dword v[6:7], v13, off
	v_fma_f32 v13, v1, v13, v14
	v_lshl_add_u64 v[6:7], v[6:7], 0, s[0:1]
	s_waitcnt vmcnt(7)
	global_store_dword v[6:7], v13, off
	v_fma_f32 v13, v1, v13, v15
	v_lshl_add_u64 v[6:7], v[6:7], 0, s[0:1]
	s_waitcnt vmcnt(7)
	global_store_dword v[6:7], v13, off
	v_fma_f32 v13, v1, v13, v18
	v_lshl_add_u64 v[6:7], v[6:7], 0, s[0:1]
	s_waitcnt vmcnt(7)
	global_store_dword v[6:7], v13, off
	v_fma_f32 v13, v1, v13, v19
	v_lshl_add_u64 v[6:7], v[6:7], 0, s[0:1]
	s_waitcnt vmcnt(7)
	global_store_dword v[6:7], v13, off
	v_fma_f32 v13, v1, v13, v20
	v_lshl_add_u64 v[6:7], v[6:7], 0, s[0:1]
	s_waitcnt vmcnt(7)
	global_store_dword v[6:7], v13, off
	v_fma_f32 v13, v1, v13, v21
	v_lshl_add_u64 v[6:7], v[6:7], 0, s[0:1]
	s_waitcnt vmcnt(7)
	global_store_dword v[6:7], v13, off
	v_fma_f32 v13, v1, v13, v22
	v_lshl_add_u64 v[6:7], v[6:7], 0, s[0:1]
	s_waitcnt vmcnt(7)
	global_store_dword v[6:7], v13, off
	v_fma_f32 v13, v1, v13, v5
	v_lshl_add_u64 v[6:7], v[6:7], 0, s[0:1]
	v_add_u32_e32 v11, -8, v11
	v_cmp_ne_u32_e64 s[0:1], 0, v11
	s_cmp_lg_u64 s[0:1], 0
	s_cbranch_scc1 .Lrsf_chk
	s_branch .Lrsf_done

.Lrsf_done:
	s_or_b64 exec, exec, s[20:21]
	s_or_b64 exec, exec, s[18:19]
	s_and_saveexec_b64 s[0:1], vcc
	s_cbranch_execz .LBB0_665

.LBB0_730:
	s_or_b64 exec, exec, s[0:1]
	s_mov_b32 s100, 0
	v_readlane_b32 s2, v255, 38
	s_mov_b32 s4, s54
	s_waitcnt lgkmcnt(0)
	s_barrier
	s_lshl_b32 s0, s2, 1
	v_cvt_f32_i32_e32 v0, s4
	s_add_i32 s0, s0, s4
	s_ashr_i32 s1, s0, 31
	s_lshl_b64 s[0:1], s[0:1], 2
	v_readlane_b32 s5, v255, 0
	s_add_u32 s0, s5, s0
	v_readlane_b32 s5, v255, 1
	v_mul_f32_e32 v0, 0xbe99999a, v0
	s_addc_u32 s1, s5, s1
	v_mul_f32_e32 v1, 0x3fb8aa3b, v0
	s_mov_b32 s5, 0x3fb8aa3b
	v_fma_f32 v2, v0, s5, -v1
	v_rndne_f32_e32 v3, v1
	v_fmac_f32_e32 v2, 0x32a5705f, v0
	v_sub_f32_e32 v1, v1, v3
	v_add_f32_e32 v1, v1, v2
	s_cmp_eq_u32 s2, 0
	v_exp_f32_e32 v1, v1
	v_cvt_i32_f32_e32 v2, v3
	s_movk_i32 s2, 0x280
	s_cselect_b32 s21, 0x80, 0
	s_cselect_b32 s20, s2, 0x200
	s_lshl_b32 s2, s21, 1
	s_or_b32 s22, s2, s20
	s_mov_b32 s2, 0xc2ce8ed0
	s_ashr_i32 s5, s4, 31
	v_ldexp_f32 v1, v1, v2
	v_cmp_ngt_f32_e32 vcc, s2, v0
	s_mov_b32 s2, 0x42b17218
	s_lshl_b32 s14, s4, 7
	s_bitset1_b32 s22, 10
	v_cndmask_b32_e32 v1, 0, v1, vcc
	v_cmp_nlt_f32_e32 vcc, s2, v0
	s_ashr_i32 s15, s14, 31
	s_lshl_b32 s23, s4, 3
	s_lshl_b64 s[4:5], s[4:5], 2
	v_readlane_b32 s2, v255, 4
	v_readlane_b32 s60, v252, 36
	s_add_u32 s40, s2, s4
	v_readlane_b32 s2, v255, 5
	v_readlane_b32 s62, v252, 38
	v_readlane_b32 s63, v252, 39
	s_addc_u32 s41, s2, s5
	s_lshl_b64 s[4:5], s[14:15], 2
	v_readlane_b32 s64, v252, 40
	v_readlane_b32 s65, v252, 41
	s_mov_b64 s[42:43], s[62:63]
	v_readlane_b32 s66, v252, 42
	v_readlane_b32 s67, v252, 43
	v_readlane_b32 s68, v252, 44
	v_readlane_b32 s69, v252, 45
	s_mov_b64 s[44:45], s[64:65]
	s_add_u32 s42, s42, s4
	v_cndmask_b32_e32 v0, v238, v1, vcc
	v_mov_b32_e32 v1, 0xbf4ccccd
	s_mov_b64 s[46:47], s[66:67]
	s_addc_u32 s43, s43, s5
	v_fmamk_f32 v0, v0, 0x3f19999a, v1
	s_add_u32 s44, s46, s4
	v_add_f32_e32 v195, 1.0, v0
	s_addc_u32 s45, s47, s5
	v_readlane_b32 s61, v252, 37
	v_readlane_b32 s70, v252, 46
	v_readlane_b32 s71, v252, 47
	v_readlane_b32 s72, v252, 48
	v_readlane_b32 s73, v252, 49
	v_readlane_b32 s74, v252, 50
	v_readlane_b32 s75, v252, 51
	s_mov_b64 s[48:49], s[68:69]
	s_branch .LBB0_734

.LBB0_734:
	s_mul_i32 s4, s100, s92
	s_add_u32 s4, s4, s101
	s_add_u32 s100, s100, 1
	s_cmpk_lt_u32 s4, 0x400
	s_cbranch_scc0 .Lp4_dyn
	s_bfe_u32 s5, s4, 0x50003
	s_and_b32 s52, s4, 7
	s_lshl_b32 s52, s52, 6
	s_or_b32 s52, s52, s5
	s_bfe_u32 s5, s4, 0x10008
	s_lshl_b32 s5, s5, 5
	s_or_b32 s52, s52, s5
	s_and_b32 s5, s4, 0x200
	s_or_b32 s52, s52, s5
	v_mov_b32_e32 v0, s52
	s_mov_b64 s[4:5], -1
	s_branch .Lp4_have_t

.LBB0_737:
	s_or_b64 exec, exec, s[14:15]
	s_waitcnt vmcnt(0)
	v_readfirstlane_b32 s2, v1
	s_nop 1
	v_add_u32_e32 v0, s2, v0
	v_add_u32_e32 v0, 0x400, v0
	ds_write_b32 v223, v0

.Lp4_have_t:
	v_cmp_le_i32_e32 vcc, s22, v0
	v_readfirstlane_b32 s52, v0
	s_cbranch_vccnz .LBB0_733
	s_cmpk_gt_i32 s52, 0x1ff
	s_cbranch_scc0 .LBB0_794
	s_cmpk_gt_u32 s52, 0x3ff
	s_cbranch_scc0 .LBB0_777
	s_add_i32 s50, s52, 0xfffffc00
	s_cmp_ge_i32 s50, s20
	s_cbranch_scc0 .LBB0_768
	s_sub_i32 s51, s50, s20
	s_cmp_ge_i32 s51, s21
	s_cbranch_scc0 .LBB0_758
	s_sub_i32 s2, s51, s21
	s_lshr_b32 s2, s2, 3
	s_lshl_b32 s53, s52, 7
	s_lshl_b32 s4, s2, 8
	s_and_b32 s5, s53, 0x80
	v_mov_b32_e32 v136, v184
	s_or_b32 s5, s4, s5
	s_addk_i32 s5, 0x4000
	v_ashrrev_i32_e32 v0, 1, v136
	v_readlane_b32 s14, v254, 54
	v_and_b32_e32 v0, 0xffffffe0, v0
	v_and_or_b32 v1, v136, 31, s5
	v_readlane_b32 s15, v254, 55
	v_add_u32_e32 v2, v1, v0
	s_lshl_b32 s5, s52, 6
	v_mov_b64_e32 v[0:1], s[14:15]
	s_addk_i32 s4, 0x4800
	v_mad_i64_i32 v[0:1], s[14:15], v2, s36, v[0:1]
	s_and_b32 s46, s5, 0x180
	s_mov_b32 s5, s3
	s_lshl_b32 s18, s46, 1
	s_lshl_b64 s[14:15], s[4:5], 10
	v_readlane_b32 s4, v253, 13
	v_readlane_b32 s5, v253, 14
	s_add_u32 s4, s4, s14
	v_mov_b32_e32 v10, v184
	s_mov_b32 s19, s3
	s_addc_u32 s5, s5, s15
	global_load_dword v151, v191, s[40:41]
	v_lshl_add_u64 v[138:139], v[0:1], 0, s[18:19]
	v_lshrrev_b32_e32 v11, 1, v10
	s_add_u32 s18, s4, s18
	v_and_b32_e32 v190, 16, v11
	s_addc_u32 s19, s5, 0
	s_lshl_b64 s[4:5], s[2:3], 18
	v_readlane_b32 s2, v255, 2
	v_lshl_add_u64 v[0:1], v[138:139], 0, v[190:191]
	s_add_u32 s2, s2, s4
	v_readlane_b32 s47, v255, 3
	global_load_dwordx4 v[108:111], v[0:1], off
	global_load_dwordx4 v[104:107], v[0:1], off offset:32
	global_load_dwordx4 v[100:103], v[0:1], off offset:64
	global_load_dwordx4 v[96:99], v[0:1], off offset:96
	v_lshlrev_b32_e32 v1, 4, v10
	s_addc_u32 s47, s47, s5
	s_lshl_b32 s46, s46, 9
	v_ashrrev_i32_e32 v2, 1, v10
	v_and_b32_e32 v4, 48, v1
	v_lshlrev_b32_e32 v1, 6, v10
	s_add_u32 s46, s2, s46
	s_movk_i32 s2, 0x90
	v_and_b32_e32 v6, 64, v1
	v_ashrrev_i32_e32 v3, 31, v2
	s_addc_u32 s47, s47, 0
	v_ashrrev_i32_e32 v0, 2, v10
	v_mad_u64_u32 v[142:143], s[48:49], v2, s2, v[6:7]
	v_lshlrev_b64 v[2:3], 9, v[2:3]
	v_lshl_add_u64 v[8:9], s[46:47], 0, v[2:3]
	v_mov_b32_e32 v7, v191
	v_ashrrev_i32_e32 v1, 31, v0
	v_mad_u64_u32 v[140:141], s[48:49], v0, s2, v[4:5]
	v_lshl_add_u64 v[6:7], v[8:9], 0, v[6:7]
	v_lshlrev_b64 v[0:1], 10, v[0:1]
	global_load_dwordx4 v[112:115], v[6:7], off offset:48
	global_load_dwordx4 v[116:119], v[6:7], off offset:32
	global_load_dwordx4 v[120:123], v[6:7], off offset:16
	global_load_dwordx4 v[124:127], v[6:7], off
	v_lshl_add_u64 v[6:7], s[18:19], 0, v[0:1]
	v_mov_b32_e32 v5, v191
	v_lshl_add_u64 v[4:5], v[6:7], 0, v[4:5]
	global_load_dwordx4 v[128:131], v[4:5], off offset:64
	global_load_dwordx4 v[132:135], v[4:5], off
	v_and_b32_e32 v4, 31, v10
	v_mul_u32_u24_e32 v16, 0x90, v4
	v_and_b32_e32 v4, 3, v10
	s_lshl_b32 s48, s52, 15
	v_lshlrev_b32_e32 v6, 1, v10
	v_lshl_add_u64 v[0:1], v[0:1], 0, s[14:15]
	s_and_b32 s2, s53, 0x300
	v_lshlrev_b32_e32 v4, 4, v4
	v_readlane_b32 s60, v252, 4
	s_and_b32 s48, s48, 0x30000
	v_and_b32_e32 v5, 19, v10
	v_and_b32_e32 v6, 8, v6
	v_and_b32_e32 v7, 4, v11
	v_or3_b32 v0, v0, s2, v4
	v_readlane_b32 s74, v252, 18
	v_readlane_b32 s75, v252, 19
	s_or_b32 s4, s4, s48
	v_or3_b32 v5, v5, v6, v7
	v_cmp_lt_i32_e32 vcc, v226, v225
	v_lshl_add_u64 v[144:145], s[74:75], 0, v[0:1]
	v_lshl_add_u64 v[0:1], s[4:5], 0, v[2:3]
	v_and_b32_e32 v2, 1, v10
	v_readlane_b32 s48, v255, 26
	v_cndmask_b32_e32 v6, v224, v226, vcc
	v_mul_u32_u24_e32 v17, 0x90, v5
	v_lshl_or_b32 v0, v2, 6, v0
	v_readlane_b32 s49, v255, 27
	v_mov_b32_e32 v14, v191
	v_mov_b32_e32 v15, v191
	v_lshlrev_b32_e32 v150, 2, v6
	v_lshl_add_u64 v[146:147], s[48:49], 0, v[0:1]
	v_mov_b32_e32 v0, v191
	v_mov_b32_e32 v1, v191
	v_mov_b32_e32 v2, v191
	v_mov_b32_e32 v3, v191
	v_mov_b32_e32 v4, v191
	v_mov_b32_e32 v5, v191
	v_mov_b32_e32 v6, v191
	v_mov_b32_e32 v7, v191
	v_mov_b32_e32 v8, v191
	v_mov_b32_e32 v9, v191
	v_mov_b32_e32 v10, v191
	v_mov_b32_e32 v11, v191
	v_mov_b32_e32 v12, v191
	v_mov_b32_e32 v13, v191
	v_add_u32_e32 v137, v190, v17
	v_add_u32_e32 v148, v190, v16
	v_mov_b64_e32 v[30:31], v[14:15]
	v_mov_b64_e32 v[46:47], v[14:15]
	v_mov_b64_e32 v[62:63], v[14:15]
	v_mov_b32_e32 v143, 0
	v_mov_b32_e32 v149, 0xf149f2ca
	s_mov_b64 s[48:49], 0
	v_mov_b64_e32 v[28:29], v[12:13]
	v_mov_b64_e32 v[26:27], v[10:11]
	v_mov_b64_e32 v[24:25], v[8:9]
	v_mov_b64_e32 v[22:23], v[6:7]
	v_mov_b64_e32 v[20:21], v[4:5]
	v_mov_b64_e32 v[18:19], v[2:3]
	v_mov_b64_e32 v[16:17], v[0:1]
	v_mov_b64_e32 v[44:45], v[12:13]
	v_mov_b64_e32 v[42:43], v[10:11]
	v_mov_b64_e32 v[40:41], v[8:9]
	v_mov_b64_e32 v[38:39], v[6:7]
	v_mov_b64_e32 v[36:37], v[4:5]
	v_mov_b64_e32 v[34:35], v[2:3]
	v_mov_b64_e32 v[32:33], v[0:1]
	v_mov_b64_e32 v[60:61], v[12:13]
	v_mov_b64_e32 v[58:59], v[10:11]
	v_mov_b64_e32 v[56:57], v[8:9]
	v_mov_b64_e32 v[54:55], v[6:7]
	v_mov_b64_e32 v[52:53], v[4:5]
	v_mov_b64_e32 v[50:51], v[2:3]
	v_mov_b64_e32 v[48:49], v[0:1]
	v_readlane_b32 s61, v252, 5
	v_readlane_b32 s62, v252, 6
	v_readlane_b32 s63, v252, 7
	v_readlane_b32 s64, v252, 8
	v_readlane_b32 s65, v252, 9
	v_readlane_b32 s66, v252, 10
	v_readlane_b32 s67, v252, 11
	v_readlane_b32 s68, v252, 12
	v_readlane_b32 s69, v252, 13
	v_readlane_b32 s70, v252, 14
	v_readlane_b32 s71, v252, 15
	v_readlane_b32 s72, v252, 16
	v_readlane_b32 s73, v252, 17

	.amdhsa_kernel _Z14fwd_megakernel6Params
		.amdhsa_group_segment_fixed_size 73748
		.amdhsa_private_segment_fixed_size 0
		.amdhsa_kernarg_size 512
		.amdhsa_user_sgpr_count 2
		.amdhsa_user_sgpr_dispatch_ptr 0
		.amdhsa_user_sgpr_queue_ptr 0
		.amdhsa_user_sgpr_kernarg_segment_ptr 1
		.amdhsa_user_sgpr_dispatch_id 0
		.amdhsa_user_sgpr_kernarg_preload_length 0
		.amdhsa_user_sgpr_kernarg_preload_offset 0
		.amdhsa_user_sgpr_private_segment_size 0
		.amdhsa_uses_dynamic_stack 0
		.amdhsa_enable_private_segment 0
		.amdhsa_system_sgpr_workgroup_id_x 1
		.amdhsa_system_sgpr_workgroup_id_y 0
		.amdhsa_system_sgpr_workgroup_id_z 0
		.amdhsa_system_sgpr_workgroup_info 0
		.amdhsa_system_vgpr_workitem_id 2
		.amdhsa_next_free_vgpr 256
		.amdhsa_next_free_sgpr 102
		.amdhsa_accum_offset 256
		.amdhsa_reserve_vcc 1
		.amdhsa_float_round_mode_32 0
		.amdhsa_float_round_mode_16_64 0
		.amdhsa_float_denorm_mode_32 3
		.amdhsa_float_denorm_mode_16_64 3
		.amdhsa_dx10_clamp 1
		.amdhsa_ieee_mode 1
		.amdhsa_fp16_overflow 0
		.amdhsa_tg_split 0
		.amdhsa_exception_fp_ieee_invalid_op 0
		.amdhsa_exception_fp_denorm_src 0
		.amdhsa_exception_fp_ieee_div_zero 0
		.amdhsa_exception_fp_ieee_overflow 0
		.amdhsa_exception_fp_ieee_underflow 0
		.amdhsa_exception_fp_ieee_inexact 0
		.amdhsa_exception_int_div_zero 0
	.end_amdhsa_kernel

amdhsa.kernels:
  - .agpr_count:     0
    .args:
      - .offset:         0
        .size:           256
        .value_kind:     by_value
      - .offset:         256
        .size:           4
        .value_kind:     hidden_block_count_x
      - .offset:         260
        .size:           4
        .value_kind:     hidden_block_count_y
      - .offset:         264
        .size:           4
        .value_kind:     hidden_block_count_z
      - .offset:         268
        .size:           2
        .value_kind:     hidden_group_size_x
      - .offset:         270
        .size:           2
        .value_kind:     hidden_group_size_y
      - .offset:         272
        .size:           2
        .value_kind:     hidden_group_size_z
      - .offset:         274
        .size:           2
        .value_kind:     hidden_remainder_x
      - .offset:         276
        .size:           2
        .value_kind:     hidden_remainder_y
      - .offset:         278
        .size:           2
        .value_kind:     hidden_remainder_z
      - .offset:         296
        .size:           8
        .value_kind:     hidden_global_offset_x
      - .offset:         304
        .size:           8
        .value_kind:     hidden_global_offset_y
      - .offset:         312
        .size:           8
        .value_kind:     hidden_global_offset_z
      - .offset:         320
        .size:           2
        .value_kind:     hidden_grid_dims
      - .offset:         344
        .size:           8
        .value_kind:     hidden_multigrid_sync_arg
    .group_segment_fixed_size: 73748
    .kernarg_segment_align: 8
    .kernarg_segment_size: 512
    .language:       OpenCL C
    .language_version:
      - 2
      - 0
    .max_flat_workgroup_size: 256
    .name:           _Z14fwd_megakernel6Params
    .private_segment_fixed_size: 0
    .sgpr_count:     108
    .sgpr_spill_count: 248
    .symbol:         _Z14fwd_megakernel6Params.kd
    .uniform_work_group_size: 1
    .uses_dynamic_stack: false
    .vgpr_count:     256
    .vgpr_spill_count: 0
    .wavefront_size: 64
